# PH4 tile loop re-emitted so every 8-byte instruction is 8-byte aligned (element order fma,bfe,exp,and; waits paired with s_nop)
# speedup vs baseline: 1.0060x; 1.0044x over previous
; #define LAS __attribute__((address_space(3)))
; template <bool MASK>
; DI void attn_unit(LAS unsigned char* lds, const bf16_t* qrow, const bf16_t* kbase, int kpitch, const bf16_t* vtbase, int vtpitch, int ntiles,
;                   const unsigned long long* maskp, bf16_t* orow, float c1, float c2) {
;     ...
;     for (int kt = 0; kt < ntiles; ++kt) {
;         const bool more = kt + 1 < ntiles;
;         if (more) {
;             const size_t ko = (size_t)(kt + 1) * 64 * kpitch; const int vo = (kt + 1) * 64;
;             pk[0] = *(const u32x4*)(kg0 + ko); pk[1] = *(const u32x4*)(kg1 + ko); pv[0] = *(const u32x4*)(vg0 + vo); pv[1] = *(const u32x4*)(vg1 + vo);
;         }
;         const unsigned long long mw = mw_next;
;         if (MASK && more) mw_next = maskp[(size_t)(kt + 1) * S_];
;         LAS unsigned char* buf = lds + (kt & 1) * ABUF;
;         f32x16 xs[2];
; #pragma unroll
;         for (int sub = 0; sub < 2; ++sub) {
; #pragma unroll
;             for (int i = 0; i < 16; ++i) xs[sub][i] = 0.f;
;             __builtin_amdgcn_s_setprio(1);
; #pragma unroll
;             for (int ks = 0; ks < 8; ++ks) {
;                 const bf16x8 a = *(const LAS bf16x8*)(buf + (32 * sub + r) * AK_PITCH + ks * 32 + h * 16);
;                 xs[sub] = __builtin_amdgcn_mfma_f32_32x32x16_bf16(a, qf[ks], xs[sub], 0, 0, 0);
;             }
;             __builtin_amdgcn_s_setprio(0);
;         }
; #pragma unroll
;         for (int sub = 0; sub < 2; ++sub) {
;             const unsigned mws = ((unsigned)(mw >> (32 * sub))) >> (4 * h);
;             float pe[16];
; #pragma unroll
;             for (int i = 0; i < 16; ++i) {
;                 float p = __builtin_amdgcn_exp2f(xs[sub][i] * c1 - c2);
;                 if (MASK) { const int m = __builtin_amdgcn_sbfe((int)mws, (i & 3) + 8 * (i >> 2), 1); p = __uint_as_float(__float_as_uint(p) & (unsigned)m); }
;                 l += p; pe[i] = p;
.Lat_noload:
	s_add_i32 s2, s16, s20
	s_cmp_lt_i32 s18, s2
	s_cbranch_scc0 .Lat_nomask
	s_nop 0
	v_lshl_add_u64 v[204:205], s[0:1], 0, v[172:173]
	global_load_dwordx2 v[174:175], v[204:205], off
	v_lshl_add_u64 v[172:173], v[172:173], 0, s[30:31]
.Lat_nomask:
	s_cmp_eq_u32 s20, 0
	s_cbranch_scc0 .Lat_grpb
	s_cmp_lt_i32 s18, s17
	s_cbranch_scc0 .Lat_bottom
	s_setprio 1
	s_nop 0
	v_add3_u32 v166, s21, v160, v153
	ds_read_b128 v[212:215], v166
	ds_read_b128 v[216:219], v166 offset:32
	ds_read_b128 v[220:223], v166 offset:64
	ds_read_b128 v[224:227], v166 offset:96
	ds_read_b128 v[228:231], v166 offset:128
	ds_read_b128 v[232:235], v166 offset:160
	ds_read_b128 v[236:239], v166 offset:192
	ds_read_b128 v[240:243], v166 offset:224
	ds_read_b128 v[244:247], v166 offset:8704
	ds_read_b128 v[248:251], v166 offset:8736
	ds_read_b128 v[200:203], v166 offset:8768
	ds_read_b128 v[204:207], v166 offset:8800
	ds_read_b128 v[208:211], v166 offset:8832
	ds_read_b128 v[182:185], v166 offset:8864
	s_waitcnt lgkmcnt(13)
	s_nop 0
	v_mfma_f32_32x32x16_bf16 v[80:95], v[212:215], v[112:115], 0
	s_waitcnt lgkmcnt(12)
	s_nop 0
	v_mfma_f32_32x32x16_bf16 v[80:95], v[216:219], v[116:119], v[80:95]
	ds_read_b128 v[212:215], v166 offset:8896
	ds_read_b128 v[216:219], v166 offset:8928
	s_waitcnt lgkmcnt(13)
	s_nop 0
	v_mfma_f32_32x32x16_bf16 v[80:95], v[220:223], v[120:123], v[80:95]
	s_waitcnt lgkmcnt(12)
	s_nop 0
	v_mfma_f32_32x32x16_bf16 v[80:95], v[224:227], v[124:127], v[80:95]
	s_waitcnt lgkmcnt(11)
	s_nop 0
	v_mfma_f32_32x32x16_bf16 v[80:95], v[228:231], v[128:131], v[80:95]
	s_waitcnt lgkmcnt(10)
	s_nop 0
	v_mfma_f32_32x32x16_bf16 v[80:95], v[232:235], v[132:135], v[80:95]
	s_waitcnt lgkmcnt(9)
	s_nop 0
	v_mfma_f32_32x32x16_bf16 v[80:95], v[236:239], v[136:139], v[80:95]
	s_waitcnt lgkmcnt(8)
	s_nop 0
	v_mfma_f32_32x32x16_bf16 v[80:95], v[240:243], v[140:143], v[80:95]
	s_waitcnt lgkmcnt(7)
	s_nop 0
	v_mfma_f32_32x32x16_bf16 v[64:79], v[244:247], v[112:115], 0
	s_waitcnt lgkmcnt(6)
	s_nop 0
	v_mfma_f32_32x32x16_bf16 v[64:79], v[248:251], v[116:119], v[64:79]
	s_waitcnt lgkmcnt(5)
	s_nop 0
	v_mfma_f32_32x32x16_bf16 v[64:79], v[200:203], v[120:123], v[64:79]
	s_waitcnt lgkmcnt(4)
	s_nop 0
	v_mfma_f32_32x32x16_bf16 v[64:79], v[204:207], v[124:127], v[64:79]
	s_waitcnt lgkmcnt(3)
	s_nop 0
	v_mfma_f32_32x32x16_bf16 v[64:79], v[208:211], v[128:131], v[64:79]
	s_waitcnt lgkmcnt(2)
	s_nop 0
	v_mfma_f32_32x32x16_bf16 v[64:79], v[182:185], v[132:135], v[64:79]
	s_waitcnt lgkmcnt(1)
	s_nop 0
	v_mfma_f32_32x32x16_bf16 v[64:79], v[212:215], v[136:139], v[64:79]
	s_waitcnt lgkmcnt(0)
	s_nop 0
	v_mfma_f32_32x32x16_bf16 v[64:79], v[216:219], v[140:143], v[64:79]
	s_setprio 0
	s_nop 0
	v_add3_u32 v166, s21, v151, v180
	v_lshrrev_b32_e32 v204, v147, v176
	v_lshrrev_b32_e32 v205, v147, v177
	v_add_u32_e32 v167, 0x4000, v166
	v_add_u32_e32 v168, 0x5000, v166
	v_add_u32_e32 v169, 0x6000, v166
	v_add_u32_e32 v199, 0x7000, v166
	ds_read2_b64 v[220:223], v167 offset0:128 offset1:130
	ds_read2_b64 v[224:227], v167 offset0:132 offset1:134
	ds_read2_b64 v[228:231], v168 offset0:160 offset1:162
	ds_read2_b64 v[232:235], v168 offset0:164 offset1:166
	ds_read2_b64 v[236:239], v169 offset0:192 offset1:194
	ds_read2_b64 v[240:243], v169 offset0:196 offset1:198
	ds_read2_b64 v[244:247], v199 offset0:224 offset1:226
	ds_read2_b64 v[248:251], v199 offset0:228 offset1:230
	v_fma_f32 v80, v80, s95, -v178
	v_bfe_i32 v206, v204, 0, 1
	v_exp_f32_e32 v80, v80
	s_nop 0
	v_fma_f32 v81, v81, s95, -v178
	v_bfe_i32 v207, v204, 1, 1
	v_exp_f32_e32 v81, v81
	v_and_b32_e32 v80, v80, v206
	v_fma_f32 v82, v82, s95, -v178
	v_bfe_i32 v208, v204, 2, 1
	v_exp_f32_e32 v82, v82
	v_and_b32_e32 v81, v81, v207
	v_fma_f32 v83, v83, s95, -v178
	v_bfe_i32 v209, v204, 3, 1
	v_exp_f32_e32 v83, v83
	v_and_b32_e32 v82, v82, v208
	v_fma_f32 v84, v84, s95, -v178
	v_bfe_i32 v210, v204, 8, 1
	v_exp_f32_e32 v84, v84
	v_and_b32_e32 v83, v83, v209
	v_fma_f32 v85, v85, s95, -v178
	v_bfe_i32 v211, v204, 9, 1
	v_exp_f32_e32 v85, v85
	v_and_b32_e32 v84, v84, v210
	v_fma_f32 v86, v86, s95, -v178
	v_bfe_i32 v206, v204, 10, 1
	v_exp_f32_e32 v86, v86
	v_and_b32_e32 v85, v85, v211
	v_fma_f32 v87, v87, s95, -v178
	v_bfe_i32 v207, v204, 11, 1
	v_exp_f32_e32 v87, v87
	v_and_b32_e32 v86, v86, v206
	v_fma_f32 v88, v88, s95, -v178
	v_bfe_i32 v208, v204, 16, 1
	v_exp_f32_e32 v88, v88
	v_and_b32_e32 v87, v87, v207
	v_fma_f32 v89, v89, s95, -v178
	v_bfe_i32 v209, v204, 17, 1
	v_exp_f32_e32 v89, v89
	v_and_b32_e32 v88, v88, v208
	v_fma_f32 v90, v90, s95, -v178
	v_bfe_i32 v210, v204, 18, 1
	v_exp_f32_e32 v90, v90
	v_and_b32_e32 v89, v89, v209
	v_fma_f32 v91, v91, s95, -v178
	v_bfe_i32 v211, v204, 19, 1
	v_exp_f32_e32 v91, v91
	v_and_b32_e32 v90, v90, v210
	v_fma_f32 v92, v92, s95, -v178
	v_bfe_i32 v206, v204, 24, 1
	v_exp_f32_e32 v92, v92
	v_and_b32_e32 v91, v91, v211
	v_fma_f32 v93, v93, s95, -v178
	v_bfe_i32 v207, v204, 25, 1
	v_exp_f32_e32 v93, v93
	v_and_b32_e32 v92, v92, v206
	v_fma_f32 v94, v94, s95, -v178
	v_bfe_i32 v208, v204, 26, 1
	v_exp_f32_e32 v94, v94
	v_and_b32_e32 v93, v93, v207
	v_fma_f32 v95, v95, s95, -v178
	v_bfe_i32 v209, v204, 27, 1
	v_exp_f32_e32 v95, v95
	v_and_b32_e32 v94, v94, v208
	v_nop
	v_and_b32_e32 v95, v95, v209
	v_cvt_pk_bf16_f32 v182, v80, v81
	v_cvt_pk_bf16_f32 v183, v82, v83
	v_cvt_pk_bf16_f32 v184, v84, v85
	v_cvt_pk_bf16_f32 v185, v86, v87
	v_cvt_pk_bf16_f32 v200, v88, v89
	v_cvt_pk_bf16_f32 v201, v90, v91
	v_cvt_pk_bf16_f32 v202, v92, v93
	v_cvt_pk_bf16_f32 v203, v94, v95
	v_pk_add_f32 v[80:81], v[80:81], v[82:83]
	v_pk_add_f32 v[84:85], v[84:85], v[86:87]
	v_pk_add_f32 v[88:89], v[88:89], v[90:91]
	v_pk_add_f32 v[92:93], v[92:93], v[94:95]
	v_pk_add_f32 v[80:81], v[80:81], v[84:85]
	v_pk_add_f32 v[88:89], v[88:89], v[92:93]
	v_pk_add_f32 v[80:81], v[80:81], v[88:89]
	v_add_f32_e32 v80, v80, v81
	v_add_f32_e32 v149, v149, v80
	s_waitcnt lgkmcnt(0)
; #define LAS __attribute__((address_space(3)))
; DI unsigned pk2(float lo, float hi) { f32x2 v = {lo, hi}; bf16x2_t b = __builtin_convertvector(v, bf16x2_t); return __builtin_bit_cast(unsigned, b); }
; template <bool MASK>
; DI void attn_unit(LAS unsigned char* lds, const bf16_t* qrow, const bf16_t* kbase, int kpitch, const bf16_t* vtbase, int vtpitch, int ntiles,
;                   const unsigned long long* maskp, bf16_t* orow, float c1, float c2) {
;     ...
;         for (int sub = 0; sub < 2; ++sub) {
;             const unsigned mws = ((unsigned)(mw >> (32 * sub))) >> (4 * h);
;             float pe[16];
; #pragma unroll
;             for (int i = 0; i < 16; ++i) {
;                 float p = __builtin_amdgcn_exp2f(xs[sub][i] * c1 - c2);
;                 if (MASK) { const int m = __builtin_amdgcn_sbfe((int)mws, (i & 3) + 8 * (i >> 2), 1); p = __uint_as_float(__float_as_uint(p) & (unsigned)m); }
;                 l += p; pe[i] = p;
;             }
;             u32x4 p0, p1;
;             p0.x = pk2(pe[0], pe[1]); p0.y = pk2(pe[2], pe[3]); p0.z = pk2(pe[4], pe[5]); p0.w = pk2(pe[6], pe[7]);
;             p1.x = pk2(pe[8], pe[9]); p1.y = pk2(pe[10], pe[11]); p1.z = pk2(pe[12], pe[13]); p1.w = pk2(pe[14], pe[15]);
;             const bf16x8 pb0 = __builtin_bit_cast(bf16x8, p0), pb1 = __builtin_bit_cast(bf16x8, p1);
; #pragma unroll
;             for (int dt = 0; dt < 4; ++dt) {
;                 const LAS unsigned char* vp = buf + AK_BYTES + (32 * dt + r) * AV_PITCH + (32 * sub + 4 * h) * 2;
;                 const s16x4 lo0 = *(const LAS s16x4*)(vp), hi0 = *(const LAS s16x4*)(vp + 16);
;                 const s16x4 lo1 = *(const LAS s16x4*)(vp + 32), hi1 = *(const LAS s16x4*)(vp + 48);
;                 const bf16x8 va0 = __builtin_shufflevector(lo0, hi0, 0, 1, 2, 3, 4, 5, 6, 7);
;                 const bf16x8 va1 = __builtin_shufflevector(lo1, hi1, 0, 1, 2, 3, 4, 5, 6, 7);
;                 o[dt] = __builtin_amdgcn_mfma_f32_32x32x16_bf16(va0, pb0, o[dt], 0, 0, 0);
;                 o[dt] = __builtin_amdgcn_mfma_f32_32x32x16_bf16(va1, pb1, o[dt], 0, 0, 0);
;             }
	s_nop 0
	v_mfma_f32_32x32x16_bf16 v[48:63], v[220:223], v[182:185], v[48:63]
	v_fma_f32 v64, v64, s95, -v178
	v_bfe_i32 v206, v205, 0, 1
	v_exp_f32_e32 v64, v64
	s_nop 0
	v_fma_f32 v65, v65, s95, -v178
	v_bfe_i32 v207, v205, 1, 1
	v_exp_f32_e32 v65, v65
	v_and_b32_e32 v64, v64, v206
	v_fma_f32 v66, v66, s95, -v178
	v_mfma_f32_32x32x16_bf16 v[48:63], v[224:227], v[200:203], v[48:63]
	v_bfe_i32 v208, v205, 2, 1
	v_exp_f32_e32 v66, v66
	v_and_b32_e32 v65, v65, v207
	v_fma_f32 v67, v67, s95, -v178
	v_bfe_i32 v209, v205, 3, 1
	v_exp_f32_e32 v67, v67
	v_and_b32_e32 v66, v66, v208
	v_fma_f32 v68, v68, s95, -v178
	v_mfma_f32_32x32x16_bf16 v[32:47], v[228:231], v[182:185], v[32:47]
	v_bfe_i32 v210, v205, 8, 1
	v_exp_f32_e32 v68, v68
	v_and_b32_e32 v67, v67, v209
	v_fma_f32 v69, v69, s95, -v178
	v_bfe_i32 v211, v205, 9, 1
	v_exp_f32_e32 v69, v69
	v_and_b32_e32 v68, v68, v210
	v_fma_f32 v70, v70, s95, -v178
	v_mfma_f32_32x32x16_bf16 v[32:47], v[232:235], v[200:203], v[32:47]
	v_bfe_i32 v206, v205, 10, 1
	v_exp_f32_e32 v70, v70
	v_and_b32_e32 v69, v69, v211
	v_fma_f32 v71, v71, s95, -v178
	v_bfe_i32 v207, v205, 11, 1
	v_exp_f32_e32 v71, v71
	v_and_b32_e32 v70, v70, v206
	v_fma_f32 v72, v72, s95, -v178
	v_mfma_f32_32x32x16_bf16 v[16:31], v[236:239], v[182:185], v[16:31]
	v_bfe_i32 v208, v205, 16, 1
	v_exp_f32_e32 v72, v72
	v_and_b32_e32 v71, v71, v207
	v_fma_f32 v73, v73, s95, -v178
	v_bfe_i32 v209, v205, 17, 1
	v_exp_f32_e32 v73, v73
	v_and_b32_e32 v72, v72, v208
	v_fma_f32 v74, v74, s95, -v178
	v_mfma_f32_32x32x16_bf16 v[16:31], v[240:243], v[200:203], v[16:31]
	v_bfe_i32 v210, v205, 18, 1
	v_exp_f32_e32 v74, v74
	v_and_b32_e32 v73, v73, v209
	v_fma_f32 v75, v75, s95, -v178
	v_bfe_i32 v211, v205, 19, 1
	v_exp_f32_e32 v75, v75
	v_and_b32_e32 v74, v74, v210
	v_fma_f32 v76, v76, s95, -v178
	v_mfma_f32_32x32x16_bf16 v[0:15], v[244:247], v[182:185], v[0:15]
	v_bfe_i32 v206, v205, 24, 1
	v_exp_f32_e32 v76, v76
	v_and_b32_e32 v75, v75, v211
	v_fma_f32 v77, v77, s95, -v178
	v_bfe_i32 v207, v205, 25, 1
	v_exp_f32_e32 v77, v77
	v_and_b32_e32 v76, v76, v206
	v_fma_f32 v78, v78, s95, -v178
	v_mfma_f32_32x32x16_bf16 v[0:15], v[248:251], v[200:203], v[0:15]
	ds_read2_b64 v[220:223], v167 offset0:136 offset1:138
	ds_read2_b64 v[224:227], v167 offset0:140 offset1:142
	ds_read2_b64 v[228:231], v168 offset0:168 offset1:170
	ds_read2_b64 v[232:235], v168 offset0:172 offset1:174
	ds_read2_b64 v[236:239], v169 offset0:200 offset1:202
	ds_read2_b64 v[240:243], v169 offset0:204 offset1:206
	ds_read2_b64 v[244:247], v199 offset0:232 offset1:234
	ds_read2_b64 v[248:251], v199 offset0:236 offset1:238
	v_bfe_i32 v208, v205, 26, 1
	v_exp_f32_e32 v78, v78
	v_and_b32_e32 v77, v77, v207
	v_fma_f32 v79, v79, s95, -v178
	v_bfe_i32 v209, v205, 27, 1
	v_exp_f32_e32 v79, v79
	v_and_b32_e32 v78, v78, v208
	v_nop
	v_and_b32_e32 v79, v79, v209
	v_cvt_pk_bf16_f32 v212, v64, v65
	v_cvt_pk_bf16_f32 v213, v66, v67
	v_cvt_pk_bf16_f32 v214, v68, v69
	v_cvt_pk_bf16_f32 v215, v70, v71
	v_cvt_pk_bf16_f32 v216, v72, v73
	v_cvt_pk_bf16_f32 v217, v74, v75
	v_cvt_pk_bf16_f32 v218, v76, v77
	v_cvt_pk_bf16_f32 v219, v78, v79
	v_pk_add_f32 v[64:65], v[64:65], v[66:67]
	v_pk_add_f32 v[68:69], v[68:69], v[70:71]
	v_pk_add_f32 v[72:73], v[72:73], v[74:75]
	v_pk_add_f32 v[76:77], v[76:77], v[78:79]
	v_pk_add_f32 v[64:65], v[64:65], v[68:69]
	v_pk_add_f32 v[72:73], v[72:73], v[76:77]
	v_pk_add_f32 v[64:65], v[64:65], v[72:73]
	v_add_f32_e32 v64, v64, v65
	v_add_f32_e32 v149, v149, v64
	s_waitcnt lgkmcnt(0)
	s_nop 0
	v_mfma_f32_32x32x16_bf16 v[48:63], v[220:223], v[212:215], v[48:63]
	v_mfma_f32_32x32x16_bf16 v[48:63], v[224:227], v[216:219], v[48:63]
	v_mfma_f32_32x32x16_bf16 v[32:47], v[228:231], v[212:215], v[32:47]
	v_mfma_f32_32x32x16_bf16 v[32:47], v[232:235], v[216:219], v[32:47]
	v_mfma_f32_32x32x16_bf16 v[16:31], v[236:239], v[212:215], v[16:31]
	v_mfma_f32_32x32x16_bf16 v[16:31], v[240:243], v[216:219], v[16:31]
	v_mfma_f32_32x32x16_bf16 v[0:15], v[244:247], v[212:215], v[0:15]
	v_mfma_f32_32x32x16_bf16 v[0:15], v[248:251], v[216:219], v[0:15]
	s_branch .Lat_bottom
.Lat_grpb:
	s_cmp_eq_u32 s18, 0
	s_cbranch_scc1 .Lat_grpb_qk
	s_nop 0
	v_add3_u32 v166, s24, v151, v180
	v_lshrrev_b32_e32 v204, v147, v176
	v_lshrrev_b32_e32 v205, v147, v177
	v_add_u32_e32 v167, 0x4000, v166
	v_add_u32_e32 v168, 0x5000, v166
	v_add_u32_e32 v169, 0x6000, v166
	v_add_u32_e32 v199, 0x7000, v166
	ds_read2_b64 v[220:223], v167 offset0:128 offset1:130
	ds_read2_b64 v[224:227], v167 offset0:132 offset1:134
	ds_read2_b64 v[228:231], v168 offset0:160 offset1:162
	ds_read2_b64 v[232:235], v168 offset0:164 offset1:166
	ds_read2_b64 v[236:239], v169 offset0:192 offset1:194
	ds_read2_b64 v[240:243], v169 offset0:196 offset1:198
	ds_read2_b64 v[244:247], v199 offset0:224 offset1:226
	ds_read2_b64 v[248:251], v199 offset0:228 offset1:230
	v_fma_f32 v80, v80, s95, -v178
	v_bfe_i32 v206, v204, 0, 1
	v_exp_f32_e32 v80, v80
	s_nop 0
	v_fma_f32 v81, v81, s95, -v178
	v_bfe_i32 v207, v204, 1, 1
	v_exp_f32_e32 v81, v81
	v_and_b32_e32 v80, v80, v206
	v_fma_f32 v82, v82, s95, -v178
	v_bfe_i32 v208, v204, 2, 1
	v_exp_f32_e32 v82, v82
	v_and_b32_e32 v81, v81, v207
	v_fma_f32 v83, v83, s95, -v178
	v_bfe_i32 v209, v204, 3, 1
	v_exp_f32_e32 v83, v83
	v_and_b32_e32 v82, v82, v208
	v_fma_f32 v84, v84, s95, -v178
	v_bfe_i32 v210, v204, 8, 1
	v_exp_f32_e32 v84, v84
	v_and_b32_e32 v83, v83, v209
	v_fma_f32 v85, v85, s95, -v178
	v_bfe_i32 v211, v204, 9, 1
	v_exp_f32_e32 v85, v85
	v_and_b32_e32 v84, v84, v210
	v_fma_f32 v86, v86, s95, -v178
	v_bfe_i32 v206, v204, 10, 1
	v_exp_f32_e32 v86, v86
	v_and_b32_e32 v85, v85, v211
	v_fma_f32 v87, v87, s95, -v178
; #define LAS __attribute__((address_space(3)))
; DI unsigned pk2(float lo, float hi) { f32x2 v = {lo, hi}; bf16x2_t b = __builtin_convertvector(v, bf16x2_t); return __builtin_bit_cast(unsigned, b); }
; template <bool MASK>
; DI void attn_unit(LAS unsigned char* lds, const bf16_t* qrow, const bf16_t* kbase, int kpitch, const bf16_t* vtbase, int vtpitch, int ntiles,
;                   const unsigned long long* maskp, bf16_t* orow, float c1, float c2) {
;     ...
;         for (int sub = 0; sub < 2; ++sub) {
;             const unsigned mws = ((unsigned)(mw >> (32 * sub))) >> (4 * h);
;             float pe[16];
; #pragma unroll
;             for (int i = 0; i < 16; ++i) {
;                 float p = __builtin_amdgcn_exp2f(xs[sub][i] * c1 - c2);
;                 if (MASK) { const int m = __builtin_amdgcn_sbfe((int)mws, (i & 3) + 8 * (i >> 2), 1); p = __uint_as_float(__float_as_uint(p) & (unsigned)m); }
;                 l += p; pe[i] = p;
;             }
;             u32x4 p0, p1;
;             p0.x = pk2(pe[0], pe[1]); p0.y = pk2(pe[2], pe[3]); p0.z = pk2(pe[4], pe[5]); p0.w = pk2(pe[6], pe[7]);
;             p1.x = pk2(pe[8], pe[9]); p1.y = pk2(pe[10], pe[11]); p1.z = pk2(pe[12], pe[13]); p1.w = pk2(pe[14], pe[15]);
;             const bf16x8 pb0 = __builtin_bit_cast(bf16x8, p0), pb1 = __builtin_bit_cast(bf16x8, p1);
; #pragma unroll
;             for (int dt = 0; dt < 4; ++dt) {
;                 const LAS unsigned char* vp = buf + AK_BYTES + (32 * dt + r) * AV_PITCH + (32 * sub + 4 * h) * 2;
;                 const s16x4 lo0 = *(const LAS s16x4*)(vp), hi0 = *(const LAS s16x4*)(vp + 16);
;                 const s16x4 lo1 = *(const LAS s16x4*)(vp + 32), hi1 = *(const LAS s16x4*)(vp + 48);
;                 const bf16x8 va0 = __builtin_shufflevector(lo0, hi0, 0, 1, 2, 3, 4, 5, 6, 7);
;                 const bf16x8 va1 = __builtin_shufflevector(lo1, hi1, 0, 1, 2, 3, 4, 5, 6, 7);
;                 o[dt] = __builtin_amdgcn_mfma_f32_32x32x16_bf16(va0, pb0, o[dt], 0, 0, 0);
;                 o[dt] = __builtin_amdgcn_mfma_f32_32x32x16_bf16(va1, pb1, o[dt], 0, 0, 0);
;             }
	v_bfe_i32 v207, v204, 11, 1
	v_exp_f32_e32 v87, v87
	v_and_b32_e32 v86, v86, v206
	v_fma_f32 v88, v88, s95, -v178
	v_bfe_i32 v208, v204, 16, 1
	v_exp_f32_e32 v88, v88
	v_and_b32_e32 v87, v87, v207
	v_fma_f32 v89, v89, s95, -v178
	v_bfe_i32 v209, v204, 17, 1
	v_exp_f32_e32 v89, v89
	v_and_b32_e32 v88, v88, v208
	v_fma_f32 v90, v90, s95, -v178
	v_bfe_i32 v210, v204, 18, 1
	v_exp_f32_e32 v90, v90
	v_and_b32_e32 v89, v89, v209
	v_fma_f32 v91, v91, s95, -v178
	v_bfe_i32 v211, v204, 19, 1
	v_exp_f32_e32 v91, v91
	v_and_b32_e32 v90, v90, v210
	v_fma_f32 v92, v92, s95, -v178
	v_bfe_i32 v206, v204, 24, 1
	v_exp_f32_e32 v92, v92
	v_and_b32_e32 v91, v91, v211
	v_fma_f32 v93, v93, s95, -v178
	v_bfe_i32 v207, v204, 25, 1
	v_exp_f32_e32 v93, v93
	v_and_b32_e32 v92, v92, v206
	v_fma_f32 v94, v94, s95, -v178
	v_bfe_i32 v208, v204, 26, 1
	v_exp_f32_e32 v94, v94
	v_and_b32_e32 v93, v93, v207
	v_fma_f32 v95, v95, s95, -v178
	v_bfe_i32 v209, v204, 27, 1
	v_exp_f32_e32 v95, v95
	v_and_b32_e32 v94, v94, v208
	v_nop
	v_and_b32_e32 v95, v95, v209
	v_cvt_pk_bf16_f32 v182, v80, v81
	v_cvt_pk_bf16_f32 v183, v82, v83
	v_cvt_pk_bf16_f32 v184, v84, v85
	v_cvt_pk_bf16_f32 v185, v86, v87
	v_cvt_pk_bf16_f32 v200, v88, v89
	v_cvt_pk_bf16_f32 v201, v90, v91
	v_cvt_pk_bf16_f32 v202, v92, v93
	v_cvt_pk_bf16_f32 v203, v94, v95
	v_pk_add_f32 v[80:81], v[80:81], v[82:83]
	v_pk_add_f32 v[84:85], v[84:85], v[86:87]
	v_pk_add_f32 v[88:89], v[88:89], v[90:91]
	v_pk_add_f32 v[92:93], v[92:93], v[94:95]
	v_pk_add_f32 v[80:81], v[80:81], v[84:85]
	v_pk_add_f32 v[88:89], v[88:89], v[92:93]
	v_pk_add_f32 v[80:81], v[80:81], v[88:89]
	v_add_f32_e32 v80, v80, v81
	v_add_f32_e32 v149, v149, v80
	s_waitcnt lgkmcnt(0)
	s_nop 0
	v_mfma_f32_32x32x16_bf16 v[48:63], v[220:223], v[182:185], v[48:63]
	v_fma_f32 v64, v64, s95, -v178
	v_bfe_i32 v206, v205, 0, 1
	v_exp_f32_e32 v64, v64
	s_nop 0
	v_fma_f32 v65, v65, s95, -v178
	v_bfe_i32 v207, v205, 1, 1
	v_exp_f32_e32 v65, v65
	v_and_b32_e32 v64, v64, v206
	v_fma_f32 v66, v66, s95, -v178
	v_mfma_f32_32x32x16_bf16 v[48:63], v[224:227], v[200:203], v[48:63]
	v_bfe_i32 v208, v205, 2, 1
	v_exp_f32_e32 v66, v66
	v_and_b32_e32 v65, v65, v207
	v_fma_f32 v67, v67, s95, -v178
	v_bfe_i32 v209, v205, 3, 1
	v_exp_f32_e32 v67, v67
	v_and_b32_e32 v66, v66, v208
	v_fma_f32 v68, v68, s95, -v178
	v_mfma_f32_32x32x16_bf16 v[32:47], v[228:231], v[182:185], v[32:47]
	v_bfe_i32 v210, v205, 8, 1
	v_exp_f32_e32 v68, v68
	v_and_b32_e32 v67, v67, v209
	v_fma_f32 v69, v69, s95, -v178
	v_bfe_i32 v211, v205, 9, 1
	v_exp_f32_e32 v69, v69
	v_and_b32_e32 v68, v68, v210
	v_fma_f32 v70, v70, s95, -v178
	v_mfma_f32_32x32x16_bf16 v[32:47], v[232:235], v[200:203], v[32:47]
	v_bfe_i32 v206, v205, 10, 1
	v_exp_f32_e32 v70, v70
	v_and_b32_e32 v69, v69, v211
	v_fma_f32 v71, v71, s95, -v178
	v_bfe_i32 v207, v205, 11, 1
	v_exp_f32_e32 v71, v71
	v_and_b32_e32 v70, v70, v206
	v_fma_f32 v72, v72, s95, -v178
	v_mfma_f32_32x32x16_bf16 v[16:31], v[236:239], v[182:185], v[16:31]
	v_bfe_i32 v208, v205, 16, 1
	v_exp_f32_e32 v72, v72
	v_and_b32_e32 v71, v71, v207
	v_fma_f32 v73, v73, s95, -v178
	v_bfe_i32 v209, v205, 17, 1
	v_exp_f32_e32 v73, v73
	v_and_b32_e32 v72, v72, v208
	v_fma_f32 v74, v74, s95, -v178
	v_mfma_f32_32x32x16_bf16 v[16:31], v[240:243], v[200:203], v[16:31]
	v_bfe_i32 v210, v205, 18, 1
	v_exp_f32_e32 v74, v74
	v_and_b32_e32 v73, v73, v209
	v_fma_f32 v75, v75, s95, -v178
	v_bfe_i32 v211, v205, 19, 1
	v_exp_f32_e32 v75, v75
	v_and_b32_e32 v74, v74, v210
	v_fma_f32 v76, v76, s95, -v178
	v_mfma_f32_32x32x16_bf16 v[0:15], v[244:247], v[182:185], v[0:15]
	v_bfe_i32 v206, v205, 24, 1
	v_exp_f32_e32 v76, v76
	v_and_b32_e32 v75, v75, v211
	v_fma_f32 v77, v77, s95, -v178
	v_bfe_i32 v207, v205, 25, 1
	v_exp_f32_e32 v77, v77
	v_and_b32_e32 v76, v76, v206
	v_fma_f32 v78, v78, s95, -v178
	v_mfma_f32_32x32x16_bf16 v[0:15], v[248:251], v[200:203], v[0:15]
	ds_read2_b64 v[220:223], v167 offset0:136 offset1:138
	ds_read2_b64 v[224:227], v167 offset0:140 offset1:142
	ds_read2_b64 v[228:231], v168 offset0:168 offset1:170
	ds_read2_b64 v[232:235], v168 offset0:172 offset1:174
	ds_read2_b64 v[236:239], v169 offset0:200 offset1:202
	ds_read2_b64 v[240:243], v169 offset0:204 offset1:206
	ds_read2_b64 v[244:247], v199 offset0:232 offset1:234
	ds_read2_b64 v[248:251], v199 offset0:236 offset1:238
	v_bfe_i32 v208, v205, 26, 1
	v_exp_f32_e32 v78, v78
	v_and_b32_e32 v77, v77, v207
	v_fma_f32 v79, v79, s95, -v178
	v_bfe_i32 v209, v205, 27, 1
	v_exp_f32_e32 v79, v79
	v_and_b32_e32 v78, v78, v208
	v_nop
	v_and_b32_e32 v79, v79, v209
	v_cvt_pk_bf16_f32 v212, v64, v65
	v_cvt_pk_bf16_f32 v213, v66, v67
	v_cvt_pk_bf16_f32 v214, v68, v69
	v_cvt_pk_bf16_f32 v215, v70, v71
	v_cvt_pk_bf16_f32 v216, v72, v73
	v_cvt_pk_bf16_f32 v217, v74, v75
	v_cvt_pk_bf16_f32 v218, v76, v77
	v_cvt_pk_bf16_f32 v219, v78, v79
	v_pk_add_f32 v[64:65], v[64:65], v[66:67]
	v_pk_add_f32 v[68:69], v[68:69], v[70:71]
	v_pk_add_f32 v[72:73], v[72:73], v[74:75]
	v_pk_add_f32 v[76:77], v[76:77], v[78:79]
	v_pk_add_f32 v[64:65], v[64:65], v[68:69]
	v_pk_add_f32 v[72:73], v[72:73], v[76:77]
	v_pk_add_f32 v[64:65], v[64:65], v[72:73]
	v_add_f32_e32 v64, v64, v65
	v_add_f32_e32 v149, v149, v64
	s_waitcnt lgkmcnt(0)
	s_nop 0
	v_mfma_f32_32x32x16_bf16 v[48:63], v[220:223], v[212:215], v[48:63]
	v_mfma_f32_32x32x16_bf16 v[48:63], v[224:227], v[216:219], v[48:63]
	v_mfma_f32_32x32x16_bf16 v[32:47], v[228:231], v[212:215], v[32:47]
	v_mfma_f32_32x32x16_bf16 v[32:47], v[232:235], v[216:219], v[32:47]
	v_mfma_f32_32x32x16_bf16 v[16:31], v[236:239], v[212:215], v[16:31]
	v_mfma_f32_32x32x16_bf16 v[16:31], v[240:243], v[216:219], v[16:31]
	v_mfma_f32_32x32x16_bf16 v[0:15], v[244:247], v[212:215], v[0:15]
	v_mfma_f32_32x32x16_bf16 v[0:15], v[248:251], v[216:219], v[0:15]
; #define LAS __attribute__((address_space(3)))
; template <bool MASK>
; DI void attn_unit(LAS unsigned char* lds, const bf16_t* qrow, const bf16_t* kbase, int kpitch, const bf16_t* vtbase, int vtpitch, int ntiles,
;                   const unsigned long long* maskp, bf16_t* orow, float c1, float c2) {
;     ...
; #pragma unroll
;         for (int sub = 0; sub < 2; ++sub) {
; #pragma unroll
;             for (int i = 0; i < 16; ++i) xs[sub][i] = 0.f;
;             __builtin_amdgcn_s_setprio(1);
; #pragma unroll
;             for (int ks = 0; ks < 8; ++ks) {
;                 const bf16x8 a = *(const LAS bf16x8*)(buf + (32 * sub + r) * AK_PITCH + ks * 32 + h * 16);
;                 xs[sub] = __builtin_amdgcn_mfma_f32_32x32x16_bf16(a, qf[ks], xs[sub], 0, 0, 0);
;             }
;             __builtin_amdgcn_s_setprio(0);
;         }
;     ...
;         if (more) {
;             LAS unsigned char* nb = lds + ((kt + 1) & 1) * ABUF;
;             *(LAS u32x4*)(nb + kl0) = pk[0]; *(LAS u32x4*)(nb + kl1) = pk[1];
;             *(LAS u32x2*)(nb + vl0) = (u32x2){pv[0].x, pv[0].y}; *(LAS u32x2*)(nb + vl0 + 8) = (u32x2){pv[0].z, pv[0].w};
;             *(LAS u32x2*)(nb + vl1) = (u32x2){pv[1].x, pv[1].y}; *(LAS u32x2*)(nb + vl1 + 8) = (u32x2){pv[1].z, pv[1].w};
;         }
.Lat_grpb_qk:
	s_cmp_lt_i32 s18, s17
	s_cbranch_scc0 .Lat_bottom
	s_setprio 1
	s_nop 0
	v_add3_u32 v166, s21, v160, v153
	ds_read_b128 v[212:215], v166
	ds_read_b128 v[216:219], v166 offset:32
	ds_read_b128 v[220:223], v166 offset:64
	ds_read_b128 v[224:227], v166 offset:96
	ds_read_b128 v[228:231], v166 offset:128
	ds_read_b128 v[232:235], v166 offset:160
	ds_read_b128 v[236:239], v166 offset:192
	ds_read_b128 v[240:243], v166 offset:224
	ds_read_b128 v[244:247], v166 offset:8704
	ds_read_b128 v[248:251], v166 offset:8736
	ds_read_b128 v[200:203], v166 offset:8768
	ds_read_b128 v[204:207], v166 offset:8800
	ds_read_b128 v[208:211], v166 offset:8832
	ds_read_b128 v[182:185], v166 offset:8864
	s_waitcnt lgkmcnt(13)
	s_nop 0
	v_mfma_f32_32x32x16_bf16 v[80:95], v[212:215], v[112:115], 0
	s_waitcnt lgkmcnt(12)
	s_nop 0
	v_mfma_f32_32x32x16_bf16 v[80:95], v[216:219], v[116:119], v[80:95]
	ds_read_b128 v[212:215], v166 offset:8896
	ds_read_b128 v[216:219], v166 offset:8928
	s_waitcnt lgkmcnt(13)
	s_nop 0
	v_mfma_f32_32x32x16_bf16 v[80:95], v[220:223], v[120:123], v[80:95]
	s_waitcnt lgkmcnt(12)
	s_nop 0
	v_mfma_f32_32x32x16_bf16 v[80:95], v[224:227], v[124:127], v[80:95]
	s_waitcnt lgkmcnt(11)
	s_nop 0
	v_mfma_f32_32x32x16_bf16 v[80:95], v[228:231], v[128:131], v[80:95]
	s_waitcnt lgkmcnt(10)
	s_nop 0
	v_mfma_f32_32x32x16_bf16 v[80:95], v[232:235], v[132:135], v[80:95]
	s_waitcnt lgkmcnt(9)
	s_nop 0
	v_mfma_f32_32x32x16_bf16 v[80:95], v[236:239], v[136:139], v[80:95]
	s_waitcnt lgkmcnt(8)
	s_nop 0
	v_mfma_f32_32x32x16_bf16 v[80:95], v[240:243], v[140:143], v[80:95]
	s_waitcnt lgkmcnt(7)
	s_nop 0
	v_mfma_f32_32x32x16_bf16 v[64:79], v[244:247], v[112:115], 0
	s_waitcnt lgkmcnt(6)
	s_nop 0
	v_mfma_f32_32x32x16_bf16 v[64:79], v[248:251], v[116:119], v[64:79]
	s_waitcnt lgkmcnt(5)
	s_nop 0
	v_mfma_f32_32x32x16_bf16 v[64:79], v[200:203], v[120:123], v[64:79]
	s_waitcnt lgkmcnt(4)
	s_nop 0
	v_mfma_f32_32x32x16_bf16 v[64:79], v[204:207], v[124:127], v[64:79]
	s_waitcnt lgkmcnt(3)
	s_nop 0
	v_mfma_f32_32x32x16_bf16 v[64:79], v[208:211], v[128:131], v[64:79]
	s_waitcnt lgkmcnt(2)
	s_nop 0
	v_mfma_f32_32x32x16_bf16 v[64:79], v[182:185], v[132:135], v[64:79]
	s_waitcnt lgkmcnt(1)
	s_nop 0
	v_mfma_f32_32x32x16_bf16 v[64:79], v[212:215], v[136:139], v[64:79]
	s_waitcnt lgkmcnt(0)
	s_nop 0
	v_mfma_f32_32x32x16_bf16 v[64:79], v[216:219], v[140:143], v[64:79]
	s_setprio 0
	s_nop 0
.Lat_bottom:
	s_cmp_lt_i32 s18, s16
	s_cbranch_scc0 .Lat_nowrite
	s_waitcnt vmcnt(1)
	v_add_u32_e32 v166, s23, v146
	ds_write_b128 v166, v[96:99]
	v_add_u32_e32 v166, s23, v148
	s_nop 0
	ds_write_b128 v166, v[100:103]
	v_add_u32_e32 v166, s23, v150
	s_nop 0
	v_add_u32_e32 v166, 0x4400, v166
	ds_write2_b64 v166, v[104:105], v[106:107] offset1:1
	v_add_u32_e32 v166, s23, v152
	s_nop 0
	v_add_u32_e32 v166, 0x4400, v166
	ds_write2_b64 v166, v[108:109], v[110:111] offset1:1
